# placement: +24 bytes of padding after the attention loop
# baseline (speedup 1.0000x reference)
.Lat_pv_done:
	s_nop 7
	v_cvt_pk_bf16_f32 v22, v240, v240
	v_cvt_pk_bf16_f32 v23, v241, v241
	v_cvt_pk_bf16_f32 v24, v242, v242
	v_cvt_pk_bf16_f32 v25, v243, v243
	v_cvt_pk_bf16_f32 v26, v244, v244
	v_cvt_pk_bf16_f32 v27, v245, v245
	v_cvt_pk_bf16_f32 v28, v246, v246
	v_cvt_pk_bf16_f32 v29, v247, v247
	v_cvt_pk_bf16_f32 v134, v248, v248
	v_cvt_pk_bf16_f32 v135, v249, v249
	v_cvt_pk_bf16_f32 v136, v250, v250
	v_cvt_pk_bf16_f32 v137, v251, v251
	v_cvt_pk_bf16_f32 v138, v120, v120
	v_cvt_pk_bf16_f32 v139, v121, v121
	v_cvt_pk_bf16_f32 v150, v122, v122
	v_cvt_pk_bf16_f32 v151, v123, v123
	global_store_short v17, v22, s[20:21]
	global_store_short v17, v23, s[20:21] offset:2048
	global_store_short v18, v24, s[20:21]
	global_store_short v18, v25, s[20:21] offset:2048
	global_store_short v17, v26, s[20:21] offset:32
	global_store_short v17, v27, s[20:21] offset:2080
	global_store_short v18, v28, s[20:21] offset:32
	global_store_short v18, v29, s[20:21] offset:2080
	global_store_short v17, v134, s[20:21] offset:64
	global_store_short v17, v135, s[20:21] offset:2112
	global_store_short v18, v136, s[20:21] offset:64
	global_store_short v18, v137, s[20:21] offset:2112
	global_store_short v17, v138, s[20:21] offset:96
	global_store_short v17, v139, s[20:21] offset:2144
	global_store_short v18, v150, s[20:21] offset:96
	global_store_short v18, v151, s[20:21] offset:2144
	s_add_u32 s3, s3, s6
	s_cmp_lt_u32 s3, 0x2000
	s_cbranch_scc1 .Lat_loop
	v_and_b32_e32 v10, 15, v0
	s_add_u32 s74, s0, 0xd8
	s_addc_u32 s75, s1, 0
	v_mov_b64_e32 v[2:3], s[74:75]
	s_mov_b64 s[64:65], exec
	s_nop 0
	s_nop 0
	s_nop 0
	s_nop 0
	s_nop 0
	s_nop 0
